# v19 plus layer-0 dense attention loop: 16x16x32 row-sum MFMA with LDS transpose in the epilogue, first two V fragment pairs hoisted to QK start with counted waits
# speedup vs baseline: 1.0129x; 1.0059x over previous
; __device__ __forceinline__ int v_st_ns(int k, int c) { return ((k >> 3) * 2 + (c >> 5)) * 512 + ((k & 7) * 32 + (c & 31)) * 2; }
; __device__ __forceinline__ int v_rd_base(int lane) { return ((lane & 3) << 3) | (((lane >> 2) & 3) << 6) | (((lane >> 4) & 1) << 5) | (((lane >> 5) & 1) << 8); }
; #define SLOAD(i, k0) do { st_[i].vs = *reinterpret_cast<const bf16x8*>(&Vh[(size_t)((k0) + sr) * LDK + sc]); \
;     st_[i].ks = *reinterpret_cast<const bf16x8*>(&Kh[(size_t)((k0) + sr) * LDK + sc]); \
;     if (DQ == 96) st_[i].kr = *reinterpret_cast<const bf16x8*>(&Kr[(size_t)((k0) + sr2) * 32 + sc2]); } while (0)
; template <int DQ, bool WIN, int LDQ, int LDK> ...
;     ...
;     const bf16_t* Qw = Qb + (size_t)(wid * 32 + r32) * LDQ + hi * 8;
; #pragma unroll
;     for (int d0 = 0; d0 < ND; ++d0) qr[d0] = *reinterpret_cast<const bf16x8*>(Qw + d0 * 16);
;     const int sr = tid >> 3, sc = (tid & 7) * 8, vst0 = v_st_ns(sr, sc);
;     const int kst0 = sr * KROW + sc * 2;
;     const int sr2 = (tid & 255) >> 2, sc2 = (tid & 3) * 8; const int kst2 = sr2 * KROW + 128 + sc2 * 2;
;     const int vb0 = (int)(uintptr_t)V_lds + v_rd_base(lane);
;     const int qrow = q0 + wid * 32 + r32;
;     struct { bf16x8 vs, ks, kr; } st_[2];
;     ...
;     f32x16 pA0, pA1, pB0, pB1; bf16x8 pa0, pa1, pa2, pa3;
;     auto finish = [&](f32x16& p0, f32x16& p1) {
;         exp16(p1);
;         pack_p_ns(p0, p1, pa0, pa1, pa2, pa3);
;     };
;     auto pv = [&](int vb) {
;         pv_d0(o, vb, pa0, pa1, pa2, pa3);
;     };
;     auto lsum_upd = [&]() {
;         lsum = __builtin_amdgcn_mfma_f32_32x32x16_bf16(pa0, ones8, lsum, 0, 0, 0);
;         lsum = __builtin_amdgcn_mfma_f32_32x32x16_bf16(pa1, ones8, lsum, 0, 0, 0);
;         lsum = __builtin_amdgcn_mfma_f32_32x32x16_bf16(pa2, ones8, lsum, 0, 0, 0);
;         lsum = __builtin_amdgcn_mfma_f32_32x32x16_bf16(pa3, ones8, lsum, 0, 0, 0);
;     };
;     constexpr int SE = 0, SO = 1;
;     SLOAD(SE, KBASE(0)); SLOAD(SO, KBASE(1));
;     SWAIT(); SWRITE(0, SE); __syncthreads();
;     qkt<DQ>(pA0, pA1, K_lds, qr, zero16, r32, hi);
;     if (WIN) win_mask(pA0, pA1, qrow - KBASE(0), hi);
;     { const float pm = row_max32(pA0, pA1); m_ref = (pm > -1e37f) ? pm : 0.f;
; #pragma unroll
;       for (int r = 0; r < 16; ++r) { minit[r] = -m_ref; pA0[r] -= m_ref; pA1[r] -= m_ref; } }
;     exp16(pA0);
.LBB0_491:
	s_or_b64 exec, exec, s[0:1]
	s_or_b32 s10, s65, s63
	s_mul_i32 s0, s10, 0xc00
	s_add_u32 s0, s69, s0
	s_addc_u32 s1, s70, 0
	s_lshl_b32 s11, s64, 6
	s_lshl_b32 s4, s64, 7
	s_add_u32 s6, s0, s4
	s_addc_u32 s7, s1, 0
	s_add_u32 s0, s69, s62
	s_addc_u32 s1, s70, 0
	s_lshl_b32 s4, s37, 7
	s_add_u32 s4, s0, s4
	v_ashrrev_i32_e32 v35, 3, v34
	v_lshlrev_b32_e32 v12, 3, v34
	s_addc_u32 s5, s1, 0
	v_and_b32_e32 v82, 56, v12
	v_mad_i64_i32 v[2:3], s[0:1], v35, s83, 0
	v_or_b32_e32 v2, v2, v82
	v_lshl_add_u64 v[6:7], v[2:3], 1, s[4:5]
	global_load_dwordx4 v[2:5], v[6:7], off offset:1280
	s_nop 0
	global_load_dwordx4 v[6:9], v[6:7], off offset:1024
	s_ashr_i32 s20, s20, 1
	v_mov_b32_e32 v10, s20
	v_bfe_u32 v1, v34, 5, 1
	v_bfi_b32 v13, s79, v10, v34
	v_mov_b64_e32 v[10:11], s[6:7]
	v_mad_i64_i32 v[10:11], s[0:1], v13, s78, v[10:11]
	v_lshlrev_b32_e32 v146, 4, v1
	v_lshl_add_u64 v[10:11], v[10:11], 0, v[146:147]
	global_load_dwordx4 v[126:129], v[10:11], off
	global_load_dwordx4 v[122:125], v[10:11], off offset:32
	global_load_dwordx4 v[118:121], v[10:11], off offset:64
	global_load_dwordx4 v[114:117], v[10:11], off offset:96
	v_bfe_u32 v14, v12, 5, 1
	v_lshlrev_b32_e32 v15, 5, v35
	v_and_b32_e32 v12, 24, v12
	v_lshrrev_b32_e32 v13, 5, v34
	v_add_u32_e32 v17, 64, v35
	v_and_or_b32 v12, v15, s81, v12
	v_and_b32_e32 v150, 31, v34
	v_and_or_b32 v13, v13, s80, v14
	v_mad_i64_i32 v[10:11], s[0:1], v17, s83, 0
	v_lshlrev_b32_e32 v12, 1, v12
	v_mul_lo_u32 v16, v35, s82
	s_waitcnt vmcnt(0)
	v_mad_u32_u24 v18, v150, s82, 0
	v_or_b32_e32 v10, v10, v82
	v_lshl_or_b32 v12, v13, 9, v12
	v_lshl_add_u32 v14, v82, 1, v16
	v_add_u32_e32 v156, v18, v146
	v_add_u32_e32 v158, 0, v12
	v_lshl_add_u64 v[10:11], v[10:11], 1, s[4:5]
	v_add_u32_e32 v157, 0, v14
	global_load_dwordx4 v[36:39], v[10:11], off offset:1280
	global_load_dwordx4 v[40:43], v[10:11], off offset:1024
	s_waitcnt vmcnt(2)
	v_and_b32_e32 v151, 63, v34
	s_andn2_b32 s20, s20, 31
	s_cmp_lg_u32 0, -1
	s_cselect_b32 s22, 0, 0
	s_mov_b32 s21, -1
	ds_write_b128 v158, v[2:5]
	ds_write_b128 v157, v[6:9] offset:16384
	s_waitcnt lgkmcnt(0)
	s_barrier
	ds_read_b128 v[2:5], v156 offset:16384
	ds_read_b128 v[44:47], v156 offset:16416
	s_waitcnt lgkmcnt(1)
	v_mfma_f32_32x32x16_bf16 v[18:33], v[2:5], v[126:129], 0
	ds_read_b128 v[2:5], v156 offset:20992
	ds_read_b128 v[48:51], v156 offset:21024
	s_waitcnt lgkmcnt(1)
	v_mfma_f32_32x32x16_bf16 v[2:17], v[2:5], v[126:129], 0
	v_mfma_f32_32x32x16_bf16 v[18:33], v[44:47], v[122:125], v[18:33]
	s_waitcnt lgkmcnt(0)
	v_mfma_f32_32x32x16_bf16 v[2:17], v[48:51], v[122:125], v[2:17]
	ds_read_b128 v[44:47], v156 offset:16448
	ds_read_b128 v[48:51], v156 offset:16480
	s_waitcnt lgkmcnt(1)
	v_mfma_f32_32x32x16_bf16 v[18:33], v[44:47], v[118:121], v[18:33]
	ds_read_b128 v[44:47], v156 offset:21056
	ds_read_b128 v[52:55], v156 offset:21088
	s_waitcnt lgkmcnt(2)
	v_mfma_f32_32x32x16_bf16 v[18:33], v[48:51], v[114:117], v[18:33]
	s_waitcnt lgkmcnt(1)
	v_mfma_f32_32x32x16_bf16 v[2:17], v[44:47], v[118:121], v[2:17]
	v_lshlrev_b32_e32 v44, 4, v34
	v_lshlrev_b32_e32 v45, 1, v34
	v_lshlrev_b32_e32 v46, 3, v151
	v_and_b32_e32 v44, 0xc0, v44
	v_and_b32_e32 v45, 32, v45
	v_and_or_b32 v44, v46, 24, v44
	v_and_b32_e32 v46, 0x100, v46
	v_or3_b32 v44, v44, v45, v46
	s_nop 1
	v_max_f32_e32 v45, v19, v19
	v_max_f32_e32 v46, v18, v18
	s_waitcnt lgkmcnt(0)
	v_mfma_f32_32x32x16_bf16 v[2:17], v[52:55], v[114:117], v[2:17]
	v_max_f32_e32 v45, v46, v45
	v_max3_f32 v45, v45, v20, v21
	v_max3_f32 v45, v45, v22, v23
	v_max3_f32 v45, v45, v24, v25
	v_max3_f32 v45, v45, v26, v27
	v_max3_f32 v45, v45, v28, v29
	v_max3_f32 v45, v45, v30, v31
	v_max3_f32 v45, v45, v32, v33
	s_nop 3
	v_max3_f32 v45, v45, v2, v3
	v_max3_f32 v45, v45, v4, v5
	v_max3_f32 v45, v45, v6, v7
	v_max3_f32 v45, v45, v8, v9
	v_max3_f32 v45, v45, v10, v11
	v_max3_f32 v45, v45, v12, v13
	v_max3_f32 v45, v45, v14, v15
	v_max3_f32 v45, v45, v16, v17
	v_mov_b32_e32 v46, v45
	s_nop 1
	v_permlane32_swap_b32_e32 v45, v46
	v_max_f32_e32 v46, v46, v46
	v_max_f32_e32 v45, v45, v45
	v_max_f32_e32 v45, v45, v46
	v_cmp_lt_f32_e32 vcc, s85, v45
	v_add_u32_e32 v159, s22, v44
	s_addk_i32 s22, 0x2000
	v_cndmask_b32_e32 v45, 0, v45, vcc
	v_sub_f32_e32 v66, v2, v45
	v_add_u32_e32 v2, 0x80, v35
	v_sub_f32_e32 v67, v3, v45
	v_mad_i64_i32 v[2:3], s[0:1], v2, s83, 0
	v_or_b32_e32 v2, v2, v82
	v_lshl_add_u64 v[2:3], v[2:3], 1, s[4:5]
	global_load_dwordx4 v[130:133], v[2:3], off offset:1024
	global_load_dwordx4 v[134:137], v[2:3], off offset:1280
	s_add_u32 s0, s33, s67
	s_addc_u32 s1, 0, 0
	v_sub_f32_e32 v18, v18, v45
	v_sub_f32_e32 v19, v19, v45
	v_sub_f32_e32 v20, v20, v45
	v_sub_f32_e32 v21, v21, v45
	v_sub_f32_e32 v22, v22, v45
	v_sub_f32_e32 v23, v23, v45
	v_sub_f32_e32 v24, v24, v45
	v_sub_f32_e32 v25, v25, v45
	v_sub_f32_e32 v26, v26, v45
	v_sub_f32_e32 v27, v27, v45
	v_sub_f32_e32 v28, v28, v45
	v_sub_f32_e32 v29, v29, v45
	v_sub_f32_e32 v30, v30, v45
	v_sub_f32_e32 v31, v31, v45
	v_sub_f32_e32 v32, v32, v45
	v_sub_f32_e32 v33, v33, v45
	v_sub_f32_e32 v68, v4, v45
	v_mov_b64_e32 v[2:3], s[0:1]
	v_and_b32_e32 v4, 7, v34
	v_exp_f32_e32 v138, v18
	v_exp_f32_e32 v139, v19
	v_exp_f32_e32 v162, v20
	v_exp_f32_e32 v165, v21
	v_exp_f32_e32 v163, v22
	v_exp_f32_e32 v166, v23
	v_exp_f32_e32 v164, v24
	v_exp_f32_e32 v167, v25
	v_exp_f32_e32 v140, v26
	v_exp_f32_e32 v144, v27
	v_exp_f32_e32 v141, v28
	v_exp_f32_e32 v145, v29
	v_exp_f32_e32 v142, v30
	v_exp_f32_e32 v160, v31
	v_exp_f32_e32 v143, v32
	v_exp_f32_e32 v161, v33
	v_mad_i64_i32 v[2:3], s[0:1], v35, s78, v[2:3]
	v_lshlrev_b32_e32 v146, 4, v4
	s_waitcnt vmcnt(2)
; #define SWRITE(b, i) do { *(bf16x8*)(V_lds + (b) * SHM_V + vst0) = st_[i].vs; *(bf16x8*)(K_lds + (b) * SHM_K + kst0) = st_[i].ks; \
;     if (DQ == 96) { if (tid < 256) *(bf16x8*)(K_lds + (b) * SHM_K + kst2) = st_[i].kr; } } while (0)
; #define SWAIT() do { if (DQ == 96) asm volatile("s_waitcnt vmcnt(3)" ::: "memory"); else asm volatile("s_waitcnt vmcnt(2)" ::: "memory"); } while (0)
; #define SWRITE(b, i) do { *(bf16x8*)(V_lds + (b) * SHM_V + vst0) = st_[i].vs; *(bf16x8*)(K_lds + (b) * SHM_K + kst0) = st_[i].ks; \
;     if (DQ == 96) { if (tid < 256) *(bf16x8*)(K_lds + (b) * SHM_K + kst2) = st_[i].kr; } } while (0)
; #define SWAIT() do { if (DQ == 96) asm volatile("s_waitcnt vmcnt(3)" ::: "memory"); else asm volatile("s_waitcnt vmcnt(2)" ::: "memory"); } while (0)
; template <int DQ, bool WIN, int LDQ, int LDK> ...
;     ...
;     float m_ref = 0.f; f32x16 o[2] = {}; f32x16 lsum = {}; f32x16 minit; bf16x8 qr[ND];
;     const bf16x8 ones8 = {(short)0x3F80, (short)0x3F80, (short)0x3F80, (short)0x3F80, (short)0x3F80, (short)0x3F80, (short)0x3F80, (short)0x3F80};
;     ...
;         pv(vb0 + SHM_V);
;         __syncthreads(); SWAIT(); SWRITE(1, SO);
;         lsum_upd();
;         if (WIN) win_mask(pA0, pA1, qrow - KBASE(j + 1), hi);
;         exp16(pA0);
;         __syncthreads();
	v_lshl_add_u64 v[2:3], v[2:3], 0, v[146:147]
	v_xor_b32_e32 v50, 0x80000000, v45
	v_lshl_add_u64 v[148:149], s[16:17], 0, v[2:3]
	v_mov_b32_e32 v2, 0
	v_sub_f32_e32 v81, v17, v45
	v_sub_f32_e32 v80, v16, v45
	v_sub_f32_e32 v79, v15, v45
	v_sub_f32_e32 v78, v14, v45
	v_sub_f32_e32 v77, v13, v45
	v_sub_f32_e32 v76, v12, v45
	v_sub_f32_e32 v75, v11, v45
	v_sub_f32_e32 v74, v10, v45
	v_sub_f32_e32 v73, v9, v45
	v_mov_b32_e32 v51, v50
	v_mov_b32_e32 v52, v50
	v_mov_b32_e32 v53, v50
	v_mov_b32_e32 v54, v50
	v_mov_b32_e32 v55, v50
	v_mov_b32_e32 v56, v50
	v_mov_b32_e32 v57, v50
	v_mov_b32_e32 v58, v50
	v_mov_b32_e32 v59, v50
	v_mov_b32_e32 v60, v50
	v_mov_b32_e32 v61, v50
	v_mov_b32_e32 v62, v50
	v_mov_b32_e32 v63, v50
	v_mov_b32_e32 v64, v50
	v_mov_b32_e32 v65, v50
	v_sub_f32_e32 v72, v8, v45
	v_sub_f32_e32 v71, v7, v45
	v_sub_f32_e32 v70, v6, v45
	v_sub_f32_e32 v69, v5, v45
	s_waitcnt vmcnt(3)
	ds_write_b128 v158, v[36:39] offset:8192
	s_waitcnt vmcnt(2)
	ds_write_b128 v157, v[40:43] offset:25600
	v_add_u32_e32 v155, s22, v44
	v_mov_b32_e32 v3, v2
	v_mov_b32_e32 v4, v2
	v_mov_b32_e32 v5, v2
	v_mov_b32_e32 v6, v2
	v_mov_b32_e32 v7, v2
	v_mov_b32_e32 v8, v2
	v_mov_b32_e32 v9, v2
	v_mov_b32_e32 v10, v2
	v_mov_b32_e32 v11, v2
	v_mov_b32_e32 v12, v2
	v_mov_b32_e32 v13, v2
	v_mov_b32_e32 v14, v2
	v_mov_b32_e32 v15, v2
	v_mov_b32_e32 v16, v2
	v_mov_b32_e32 v17, v2
	v_mov_b32_e32 v18, v2
	v_mov_b32_e32 v19, v2
	v_mov_b32_e32 v20, v2
	v_mov_b32_e32 v21, v2
	v_mov_b32_e32 v22, v2
	v_mov_b32_e32 v23, v2
	v_mov_b32_e32 v24, v2
	v_mov_b32_e32 v25, v2
	v_mov_b32_e32 v26, v2
	v_mov_b32_e32 v27, v2
	v_mov_b32_e32 v28, v2
	v_mov_b32_e32 v29, v2
	v_mov_b32_e32 v30, v2
	v_mov_b32_e32 v31, v2
	v_mov_b32_e32 v32, v2
	v_mov_b32_e32 v33, v2
	v_mov_b32_e32 v34, v2
	v_mov_b32_e32 v35, v2
	v_mov_b32_e32 v36, v2
	v_mov_b32_e32 v37, v2
	v_lshrrev_b32_e32 v38, 4, v151
	v_xor_b32_e32 v38, v38, v151
	v_not_b32_e32 v38, v38
	v_bfe_i32 v38, v38, 0, 1
	v_and_b32_e32 v38, 0x3f803f80, v38
	v_mov_b32_e32 v39, v38
	v_mov_b32_e32 v40, v38
	v_mov_b32_e32 v41, v38
	v_mov_b32_e32 v42, v2
	v_mov_b32_e32 v43, v2
	v_mov_b32_e32 v44, v2
	v_mov_b32_e32 v45, v2
	v_mov_b32_e32 v46, v2
	v_mov_b32_e32 v47, v2
	v_mov_b32_e32 v48, v2
	v_mov_b32_e32 v49, v2
	v_xor_b32_e32 v158, 0xc000, v158
	s_waitcnt lgkmcnt(0)
	s_barrier
	s_branch .LBB0_493
.LBB0_492:
	ds_read_b64_tr_b16 v[168:169], v155 offset:0x1000
	ds_read_b64_tr_b16 v[170:171], v155 offset:0x1400
	ds_read_b64_tr_b16 v[172:173], v155 offset:0x1800
	ds_read_b64_tr_b16 v[174:175], v155 offset:0x1c00
	ds_read_b64_tr_b16 v[160:161], v155 offset:0x200
	ds_read_b64_tr_b16 v[162:163], v155 offset:0x600
	ds_read_b64_tr_b16 v[164:165], v155 offset:0xa00
	ds_read_b64_tr_b16 v[166:167], v155 offset:0xe00
	s_nop 0
	v_mfma_f32_32x32x16_bf16 v[2:17], v[94:97], v[42:45], v[2:17]
	v_mfma_f32_32x32x16_bf16 v[2:17], v[90:93], v[46:49], v[2:17]
	s_waitcnt lgkmcnt(6)
	v_mfma_f32_32x32x16_bf16 v[2:17], v[86:89], v[168:171], v[2:17]
	ds_read_b64_tr_b16 v[168:169], v155 offset:0x1200
	ds_read_b64_tr_b16 v[170:171], v155 offset:0x1600
	s_waitcnt lgkmcnt(6)
	v_mfma_f32_32x32x16_bf16 v[2:17], v[82:85], v[172:175], v[2:17]
	ds_read_b64_tr_b16 v[176:177], v155 offset:0x1a00
	ds_read_b64_tr_b16 v[178:179], v155 offset:0x1e00
	s_waitcnt lgkmcnt(0)
	v_mfma_f32_32x32x16_bf16 v[18:33], v[94:97], v[160:163], v[18:33]
	s_waitcnt vmcnt(2)
	s_waitcnt vmcnt(1)
	ds_write_b128 v158, v[138:141] offset:8192
	s_waitcnt vmcnt(0)
	ds_write_b128 v157, v[142:145] offset:25600
	v_exp_f32_e32 v138, v98
	v_exp_f32_e32 v139, v99
	v_mfma_f32_32x32x16_bf16 v[18:33], v[90:93], v[164:167], v[18:33]
	v_exp_f32_e32 v162, v100
	v_exp_f32_e32 v165, v101
	v_exp_f32_e32 v163, v102
	v_exp_f32_e32 v166, v103
	v_exp_f32_e32 v164, v104
	v_exp_f32_e32 v167, v105
	v_exp_f32_e32 v140, v106
	v_mfma_f32_32x32x16_bf16 v[18:33], v[86:89], v[168:171], v[18:33]
	v_exp_f32_e32 v144, v107
	v_exp_f32_e32 v141, v108
	v_exp_f32_e32 v145, v109
	v_exp_f32_e32 v142, v110
	v_exp_f32_e32 v160, v111
	v_mfma_f32_16x16x32_bf16 v[34:37], v[94:97], v[38:41], v[34:37]
	v_exp_f32_e32 v143, v112
	v_exp_f32_e32 v161, v113
	v_lshl_add_u64 v[148:149], v[148:149], 0, s[18:19]
	s_and_b64 vcc, exec, s[0:1]
	s_waitcnt lgkmcnt(0)
	s_barrier
	v_mfma_f32_16x16x32_bf16 v[34:37], v[90:93], v[38:41], v[34:37]
	v_mfma_f32_16x16x32_bf16 v[34:37], v[86:89], v[38:41], v[34:37]
	v_mfma_f32_32x32x16_bf16 v[18:33], v[82:85], v[176:179], v[18:33]
	v_mfma_f32_16x16x32_bf16 v[34:37], v[82:85], v[38:41], v[34:37]
	v_xor_b32_e32 v158, 0xc000, v158
	v_xor_b32_e32 v159, 0xc000, v159
	v_xor_b32_e32 v155, 0xc000, v155
	s_cbranch_vccnz .LBB0_495
; #define SBAR() __builtin_amdgcn_sched_barrier(0)
; #define SLOAD(i, k0) do { st_[i].vs = *reinterpret_cast<const bf16x8*>(&Vh[(size_t)((k0) + sr) * LDK + sc]); \
;     st_[i].ks = *reinterpret_cast<const bf16x8*>(&Kh[(size_t)((k0) + sr) * LDK + sc]); \
;     if (DQ == 96) st_[i].kr = *reinterpret_cast<const bf16x8*>(&Kr[(size_t)((k0) + sr2) * 32 + sc2]); } while (0)
; #define SWRITE(b, i) do { *(bf16x8*)(V_lds + (b) * SHM_V + vst0) = st_[i].vs; *(bf16x8*)(K_lds + (b) * SHM_K + kst0) = st_[i].ks; \
;     if (DQ == 96) { if (tid < 256) *(bf16x8*)(K_lds + (b) * SHM_K + kst2) = st_[i].kr; } } while (0)
; #define SWAIT() do { if (DQ == 96) asm volatile("s_waitcnt vmcnt(3)" ::: "memory"); else asm volatile("s_waitcnt vmcnt(2)" ::: "memory"); } while (0)
; #define SLOAD(i, k0) do { st_[i].vs = *reinterpret_cast<const bf16x8*>(&Vh[(size_t)((k0) + sr) * LDK + sc]); \
;     st_[i].ks = *reinterpret_cast<const bf16x8*>(&Kh[(size_t)((k0) + sr) * LDK + sc]); \
;     if (DQ == 96) st_[i].kr = *reinterpret_cast<const bf16x8*>(&Kr[(size_t)((k0) + sr2) * 32 + sc2]); } while (0)
; #define SWRITE(b, i) do { *(bf16x8*)(V_lds + (b) * SHM_V + vst0) = st_[i].vs; *(bf16x8*)(K_lds + (b) * SHM_K + kst0) = st_[i].ks; \
;     if (DQ == 96) { if (tid < 256) *(bf16x8*)(K_lds + (b) * SHM_K + kst2) = st_[i].kr; } } while (0)
; template <int DQ, bool WIN, int LDQ, int LDK> ...
;     ...
;     auto lsum_upd = [&]() {
;         lsum = __builtin_amdgcn_mfma_f32_32x32x16_bf16(pa0, ones8, lsum, 0, 0, 0);
;         lsum = __builtin_amdgcn_mfma_f32_32x32x16_bf16(pa1, ones8, lsum, 0, 0, 0);
;         lsum = __builtin_amdgcn_mfma_f32_32x32x16_bf16(pa2, ones8, lsum, 0, 0, 0);
;         lsum = __builtin_amdgcn_mfma_f32_32x32x16_bf16(pa3, ones8, lsum, 0, 0, 0);
;     ...
;     for (int j = 1; j + 1 < NT; j += 2) {
;         SBAR(); qkt<DQ>(pB0, pB1, K_lds + SHM_K, qr, minit, r32, hi);
;         finish(pA0, pA1); SBAR();
;         SLOAD(SO, KBASE(j + 2)); SBAR();
;         pv(vb0);
;         __syncthreads(); SWAIT(); SWRITE(0, SE);
;         lsum_upd();
;         if (WIN) win_mask(pB0, pB1, qrow - KBASE(j), hi);
;         exp16(pB0);
;         __syncthreads();
;         SBAR(); qkt<DQ>(pA0, pA1, K_lds, qr, minit, r32, hi);
;         finish(pB0, pB1); SBAR();
;         if (j + 3 < NT) SLOAD(SE, KBASE(j + 3)); SBAR();
.LBB0_493:
	s_add_i32 s21, s21, 2
	ds_read_b64_tr_b16 v[42:43], v159 offset:0
	ds_read_b64_tr_b16 v[44:45], v159 offset:0x400
	ds_read_b64_tr_b16 v[46:47], v159 offset:0x800
	ds_read_b64_tr_b16 v[48:49], v159 offset:0xc00
	ds_read_b128 v[82:85], v156 offset:25600
	ds_read_b128 v[168:171], v156 offset:25632
	ds_read_b128 v[172:175], v156 offset:30208
	ds_read_b128 v[176:179], v156 offset:30240
	v_exp_f32_e32 v81, v81
	v_exp_f32_e32 v146, v66
	s_waitcnt lgkmcnt(3)
	v_mfma_f32_32x32x16_bf16 v[98:113], v[82:85], v[126:129], v[50:65]
	v_exp_f32_e32 v180, v67
	v_exp_f32_e32 v190, v68
	v_exp_f32_e32 v191, v73
	v_exp_f32_e32 v192, v74
	v_exp_f32_e32 v193, v75
	v_exp_f32_e32 v194, v80
	s_waitcnt lgkmcnt(1)
	v_mfma_f32_32x32x16_bf16 v[82:97], v[172:175], v[126:129], v[50:65]
	v_mfma_f32_32x32x16_bf16 v[98:113], v[168:171], v[122:125], v[98:113]
	ds_read_b128 v[168:171], v156 offset:25664
	ds_read_b128 v[172:175], v156 offset:25696
	ds_read_b128 v[182:185], v156 offset:30272
	ds_read_b128 v[186:189], v156 offset:30304
	v_cvt_pk_bf16_f32 v66, v138, v139
	v_cvt_pk_bf16_f32 v67, v162, v165
	v_cvt_pk_bf16_f32 v68, v163, v166
	s_waitcnt lgkmcnt(4)
	v_mfma_f32_32x32x16_bf16 v[82:97], v[176:179], v[122:125], v[82:97]
	v_exp_f32_e32 v176, v69
	v_exp_f32_e32 v177, v70
	v_exp_f32_e32 v178, v71
	v_exp_f32_e32 v179, v72
	v_cvt_pk_bf16_f32 v69, v164, v167
	v_cvt_pk_bf16_f32 v70, v140, v144
	v_cvt_pk_bf16_f32 v71, v141, v145
	s_waitcnt lgkmcnt(3)
	v_mfma_f32_32x32x16_bf16 v[98:113], v[168:171], v[118:121], v[98:113]
	v_exp_f32_e32 v168, v76
	v_exp_f32_e32 v169, v77
	v_exp_f32_e32 v170, v78
	v_exp_f32_e32 v171, v79
	v_cvt_pk_bf16_f32 v72, v142, v160
	v_cvt_pk_bf16_f32 v73, v143, v161
	v_cvt_pk_bf16_f32 v74, v146, v180
	s_waitcnt lgkmcnt(1)
	v_mfma_f32_32x32x16_bf16 v[82:97], v[182:185], v[118:121], v[82:97]
	v_cvt_pk_bf16_f32 v75, v190, v176
	v_cvt_pk_bf16_f32 v76, v177, v178
	v_cvt_pk_bf16_f32 v77, v179, v191
	v_cvt_pk_bf16_f32 v78, v192, v193
	v_cvt_pk_bf16_f32 v79, v168, v169
	v_cvt_pk_bf16_f32 v80, v170, v171
	v_cvt_pk_bf16_f32 v81, v194, v81
	v_mfma_f32_32x32x16_bf16 v[98:113], v[172:175], v[114:117], v[98:113]
	s_waitcnt lgkmcnt(0)
	v_mfma_f32_32x32x16_bf16 v[82:97], v[186:189], v[114:117], v[82:97]
	v_add_co_u32_e32 v142, vcc, s90, v148
	s_nop 1
	v_addc_co_u32_e32 v143, vcc, -1, v149, vcc
	global_load_dwordx4 v[138:141], v[142:143], off
	s_nop 0
	global_load_dwordx4 v[142:145], v[142:143], off offset:-256
	ds_read_b64_tr_b16 v[168:169], v159 offset:0x1000
	ds_read_b64_tr_b16 v[170:171], v159 offset:0x1400
	ds_read_b64_tr_b16 v[172:173], v159 offset:0x1800
	ds_read_b64_tr_b16 v[174:175], v159 offset:0x1c00
	ds_read_b64_tr_b16 v[160:161], v159 offset:0x200
	ds_read_b64_tr_b16 v[162:163], v159 offset:0x600
	ds_read_b64_tr_b16 v[164:165], v159 offset:0xa00
	ds_read_b64_tr_b16 v[166:167], v159 offset:0xe00
	s_nop 0
	v_mfma_f32_32x32x16_bf16 v[2:17], v[66:69], v[42:45], v[2:17]
	v_mfma_f32_32x32x16_bf16 v[2:17], v[70:73], v[46:49], v[2:17]
	s_waitcnt lgkmcnt(6)
	v_mfma_f32_32x32x16_bf16 v[2:17], v[74:77], v[168:171], v[2:17]
	ds_read_b64_tr_b16 v[168:169], v159 offset:0x1200
	ds_read_b64_tr_b16 v[170:171], v159 offset:0x1600
	s_waitcnt lgkmcnt(6)
	v_mfma_f32_32x32x16_bf16 v[2:17], v[78:81], v[172:175], v[2:17]
	ds_read_b64_tr_b16 v[176:177], v159 offset:0x1a00
	ds_read_b64_tr_b16 v[178:179], v159 offset:0x1e00
	s_waitcnt lgkmcnt(0)
	v_mfma_f32_32x32x16_bf16 v[18:33], v[66:69], v[160:163], v[18:33]
	s_waitcnt vmcnt(2)
	s_waitcnt vmcnt(2)
	ds_write_b128 v158, v[134:137]
	ds_write_b128 v157, v[130:133] offset:16384
	v_mfma_f32_16x16x32_bf16 v[34:37], v[66:69], v[38:41], v[34:37]
	v_exp_f32_e32 v146, v98
	v_exp_f32_e32 v180, v99
	v_exp_f32_e32 v182, v100
	v_exp_f32_e32 v183, v101
	v_exp_f32_e32 v184, v102
	v_exp_f32_e32 v185, v103
	v_exp_f32_e32 v186, v104
	v_mfma_f32_32x32x16_bf16 v[18:33], v[70:73], v[164:167], v[18:33]
	v_exp_f32_e32 v187, v105
	v_exp_f32_e32 v188, v106
	v_exp_f32_e32 v189, v107
	v_exp_f32_e32 v190, v108
	v_exp_f32_e32 v191, v109
	v_exp_f32_e32 v192, v110
	v_exp_f32_e32 v193, v111
	v_mfma_f32_16x16x32_bf16 v[34:37], v[70:73], v[38:41], v[34:37]
	v_exp_f32_e32 v194, v112
	v_exp_f32_e32 v195, v113
	s_waitcnt lgkmcnt(0)
	s_barrier
	v_mfma_f32_32x32x16_bf16 v[18:33], v[74:77], v[168:171], v[18:33]
	v_mfma_f32_16x16x32_bf16 v[34:37], v[74:77], v[38:41], v[34:37]
	v_mfma_f32_32x32x16_bf16 v[18:33], v[78:81], v[176:179], v[18:33]
	v_mfma_f32_16x16x32_bf16 v[34:37], v[78:81], v[38:41], v[34:37]
	ds_read_b64_tr_b16 v[42:43], v155 offset:0
	ds_read_b64_tr_b16 v[44:45], v155 offset:0x400
	ds_read_b64_tr_b16 v[46:47], v155 offset:0x800
	ds_read_b64_tr_b16 v[48:49], v155 offset:0xc00
	ds_read_b128 v[66:69], v156 offset:16384
	ds_read_b128 v[160:163], v156 offset:16416
	ds_read_b128 v[164:167], v156 offset:20992
	ds_read_b128 v[168:171], v156 offset:21024
	v_exp_f32_e32 v82, v82
	v_exp_f32_e32 v83, v83
	s_waitcnt lgkmcnt(3)
	v_mfma_f32_32x32x16_bf16 v[98:113], v[66:69], v[126:129], v[50:65]
	v_exp_f32_e32 v84, v84
	v_exp_f32_e32 v85, v85
	v_exp_f32_e32 v89, v89
	v_exp_f32_e32 v196, v91
	v_exp_f32_e32 v197, v96
	v_exp_f32_e32 v198, v97
	s_waitcnt lgkmcnt(1)
	v_mfma_f32_32x32x16_bf16 v[66:81], v[164:167], v[126:129], v[50:65]
	v_mfma_f32_32x32x16_bf16 v[98:113], v[160:163], v[122:125], v[98:113]
	ds_read_b128 v[160:163], v156 offset:16448
	ds_read_b128 v[164:167], v156 offset:16480
	ds_read_b128 v[172:175], v156 offset:21056
	ds_read_b128 v[176:179], v156 offset:21088
	s_waitcnt lgkmcnt(4)
	v_mfma_f32_32x32x16_bf16 v[66:81], v[168:171], v[122:125], v[66:81]
	v_exp_f32_e32 v168, v86
	v_exp_f32_e32 v169, v87
	v_exp_f32_e32 v170, v88
	v_exp_f32_e32 v171, v90
	s_waitcnt lgkmcnt(3)
	v_mfma_f32_32x32x16_bf16 v[98:113], v[160:163], v[118:121], v[98:113]
	v_exp_f32_e32 v160, v92
	v_exp_f32_e32 v161, v93
	v_exp_f32_e32 v162, v94
	v_exp_f32_e32 v163, v95
	v_cvt_pk_bf16_f32 v94, v146, v180
	v_cvt_pk_bf16_f32 v95, v182, v183
	v_cvt_pk_bf16_f32 v96, v184, v185
	s_waitcnt lgkmcnt(1)
	v_mfma_f32_32x32x16_bf16 v[66:81], v[172:175], v[118:121], v[66:81]
	v_cvt_pk_bf16_f32 v97, v186, v187
	v_cvt_pk_bf16_f32 v90, v188, v189
	v_cvt_pk_bf16_f32 v91, v190, v191
	v_cvt_pk_bf16_f32 v92, v192, v193
	v_cvt_pk_bf16_f32 v93, v194, v195
	v_cvt_pk_bf16_f32 v86, v82, v83
	v_cvt_pk_bf16_f32 v87, v84, v85
	v_mfma_f32_32x32x16_bf16 v[98:113], v[164:167], v[114:117], v[98:113]
	v_cvt_pk_bf16_f32 v88, v168, v169
	v_cvt_pk_bf16_f32 v89, v170, v89
	v_cvt_pk_bf16_f32 v82, v171, v196
	v_cvt_pk_bf16_f32 v83, v160, v161
	v_cvt_pk_bf16_f32 v84, v162, v163
	v_cvt_pk_bf16_f32 v85, v197, v198
	s_waitcnt lgkmcnt(0)
	v_mfma_f32_32x32x16_bf16 v[66:81], v[176:179], v[114:117], v[66:81]
	s_cmpk_gt_u32 s21, 0x7c
	s_cselect_b64 s[0:1], -1, 0
	s_and_b64 vcc, exec, s[0:1]
	s_cbranch_vccnz .LBB0_492
	global_load_dwordx4 v[134:137], v[148:149], off
	global_load_dwordx4 v[130:133], v[148:149], off offset:-256
	s_branch .LBB0_492
; #define SBAR() __builtin_amdgcn_sched_barrier(0)
; template <int DQ, bool WIN, int LDQ, int LDK> ...
;     ...
;     SBAR(); qkt<DQ>(pB0, pB1, K_lds + SHM_K, qr, minit, r32, hi);
;     finish(pA0, pA1); SBAR();
;     pv(vb0); lsum_upd();
;     if (WIN) win_mask(pB0, pB1, qrow - KBASE(NT - 1), hi);
;     exp16(pB0);
;     finish(pB0, pB1); SBAR();
;     pv(vb0 + SHM_V); lsum_upd();
.LBB0_495:
	ds_read_b128 v[98:101], v156 offset:25600
	ds_read_b128 v[102:105], v156 offset:25632
	v_exp_f32_e32 v81, v81
	v_exp_f32_e32 v130, v66
	v_exp_f32_e32 v131, v67
	s_waitcnt lgkmcnt(1)
	v_mfma_f32_32x32x16_bf16 v[82:97], v[98:101], v[126:129], v[50:65]
	ds_read_b128 v[98:101], v156 offset:30208
	ds_read_b128 v[106:109], v156 offset:30240
	v_exp_f32_e32 v132, v68
	s_waitcnt lgkmcnt(1)
	v_mfma_f32_32x32x16_bf16 v[50:65], v[98:101], v[126:129], v[50:65]
	v_mfma_f32_32x32x16_bf16 v[82:97], v[102:105], v[122:125], v[82:97]
	ds_read_b128 v[98:101], v156 offset:25664
	ds_read_b128 v[102:105], v156 offset:25696
	ds_read_b128 v[110:113], v156 offset:30272
	ds_read_b128 v[126:129], v156 offset:30304
	v_cvt_pk_bf16_f32 v66, v138, v139
	v_cvt_pk_bf16_f32 v67, v162, v165
	v_cvt_pk_bf16_f32 v68, v163, v166
	s_waitcnt lgkmcnt(4)
	v_mfma_f32_32x32x16_bf16 v[50:65], v[106:109], v[122:125], v[50:65]
	v_exp_f32_e32 v106, v69
	v_exp_f32_e32 v107, v70
	v_exp_f32_e32 v108, v71
	v_exp_f32_e32 v109, v72
	v_exp_f32_e32 v122, v73
	v_exp_f32_e32 v123, v74
	v_exp_f32_e32 v124, v75
	s_waitcnt lgkmcnt(3)
	v_mfma_f32_32x32x16_bf16 v[82:97], v[98:101], v[118:121], v[82:97]
	v_exp_f32_e32 v98, v76
	v_exp_f32_e32 v99, v77
	v_exp_f32_e32 v100, v78
	v_exp_f32_e32 v101, v79
	v_exp_f32_e32 v125, v80
	v_cvt_pk_bf16_f32 v69, v164, v167
	v_cvt_pk_bf16_f32 v70, v140, v144
	s_waitcnt lgkmcnt(1)
	v_mfma_f32_32x32x16_bf16 v[50:65], v[110:113], v[118:121], v[50:65]
	v_cvt_pk_bf16_f32 v71, v141, v145
	v_cvt_pk_bf16_f32 v72, v142, v160
	v_cvt_pk_bf16_f32 v73, v143, v161
	v_cvt_pk_bf16_f32 v74, v130, v131
	v_cvt_pk_bf16_f32 v75, v132, v106
	v_cvt_pk_bf16_f32 v76, v107, v108
	v_cvt_pk_bf16_f32 v77, v109, v122
	v_mfma_f32_32x32x16_bf16 v[82:97], v[102:105], v[114:117], v[82:97]
	v_cvt_pk_bf16_f32 v78, v123, v124
	v_cvt_pk_bf16_f32 v79, v98, v99
	v_cvt_pk_bf16_f32 v80, v100, v101
	v_cvt_pk_bf16_f32 v81, v125, v81
	s_waitcnt lgkmcnt(0)
	v_mfma_f32_32x32x16_bf16 v[50:65], v[126:129], v[114:117], v[50:65]
	ds_read_b64_tr_b16 v[98:99], v159 offset:0
	ds_read_b64_tr_b16 v[100:101], v159 offset:0x400
	ds_read_b64_tr_b16 v[102:103], v159 offset:0x800
	ds_read_b64_tr_b16 v[104:105], v159 offset:0xc00
	ds_read_b64_tr_b16 v[106:107], v159 offset:0x1000
	ds_read_b64_tr_b16 v[108:109], v159 offset:0x1400
	ds_read_b64_tr_b16 v[110:111], v159 offset:0x1800
	ds_read_b64_tr_b16 v[112:113], v159 offset:0x1c00
	s_waitcnt lgkmcnt(0)
	s_nop 0
	v_mfma_f32_32x32x16_bf16 v[2:17], v[66:69], v[98:101], v[2:17]
	ds_read_b64_tr_b16 v[98:99], v159 offset:0x200
	ds_read_b64_tr_b16 v[100:101], v159 offset:0x600
	v_mfma_f32_32x32x16_bf16 v[2:17], v[70:73], v[102:105], v[2:17]
	ds_read_b64_tr_b16 v[102:103], v159 offset:0xa00
	ds_read_b64_tr_b16 v[104:105], v159 offset:0xe00
	v_mfma_f32_32x32x16_bf16 v[2:17], v[74:77], v[106:109], v[2:17]
	ds_read_b64_tr_b16 v[106:107], v159 offset:0x1200
	ds_read_b64_tr_b16 v[108:109], v159 offset:0x1600
	ds_read_b64_tr_b16 v[114:115], v159 offset:0x1a00
	ds_read_b64_tr_b16 v[116:117], v159 offset:0x1e00
	s_waitcnt lgkmcnt(0)
	v_mfma_f32_32x32x16_bf16 v[2:17], v[78:81], v[110:113], v[2:17]
	v_mfma_f32_32x32x16_bf16 v[18:33], v[66:69], v[98:101], v[18:33]
	v_mov_b64_e32 v[100:101], s[14:15]
	v_mov_b64_e32 v[98:99], s[12:13]
	s_nop 3
	v_exp_f32_e32 v65, v65
	v_exp_f32_e32 v82, v82
	v_exp_f32_e32 v83, v83
	v_exp_f32_e32 v84, v84
	v_exp_f32_e32 v85, v85
	v_mfma_f32_16x16x32_bf16 v[34:37], v[66:69], v[38:41], v[34:37]
	v_exp_f32_e32 v86, v86
	v_exp_f32_e32 v87, v87
	v_exp_f32_e32 v88, v88
	v_exp_f32_e32 v89, v89
	v_exp_f32_e32 v90, v90
	v_exp_f32_e32 v91, v91
	v_exp_f32_e32 v92, v92
	v_mfma_f32_32x32x16_bf16 v[18:33], v[70:73], v[102:105], v[18:33]
	v_exp_f32_e32 v93, v93
	v_exp_f32_e32 v94, v94
	v_exp_f32_e32 v95, v95
	v_exp_f32_e32 v96, v96
	v_exp_f32_e32 v97, v97
	v_exp_f32_e32 v102, v50
	v_exp_f32_e32 v103, v51
	v_mfma_f32_16x16x32_bf16 v[34:37], v[70:73], v[38:41], v[34:37]
	v_exp_f32_e32 v104, v52
	v_exp_f32_e32 v105, v53
	v_exp_f32_e32 v110, v58
	v_exp_f32_e32 v111, v59
	v_exp_f32_e32 v66, v60
	v_exp_f32_e32 v67, v61
	v_exp_f32_e32 v68, v62
	v_mfma_f32_32x32x16_bf16 v[18:33], v[74:77], v[106:109], v[18:33]
	v_exp_f32_e32 v106, v54
	v_exp_f32_e32 v107, v55
	v_exp_f32_e32 v108, v56
	v_exp_f32_e32 v109, v57
	v_exp_f32_e32 v69, v63
	v_exp_f32_e32 v112, v64
	v_cvt_pk_bf16_f32 v50, v82, v83
	v_mfma_f32_16x16x32_bf16 v[34:37], v[74:77], v[38:41], v[34:37]
	v_cvt_pk_bf16_f32 v51, v84, v85
	v_cvt_pk_bf16_f32 v52, v86, v87
	v_cvt_pk_bf16_f32 v53, v88, v89
	v_cvt_pk_bf16_f32 v54, v90, v91
	v_cvt_pk_bf16_f32 v55, v92, v93
	v_cvt_pk_bf16_f32 v56, v94, v95
	v_cvt_pk_bf16_f32 v57, v96, v97
	v_mfma_f32_32x32x16_bf16 v[18:33], v[78:81], v[114:117], v[18:33]
	v_cvt_pk_bf16_f32 v58, v102, v103
	v_cvt_pk_bf16_f32 v59, v104, v105
	v_cvt_pk_bf16_f32 v60, v106, v107
	v_cvt_pk_bf16_f32 v61, v108, v109
	v_cvt_pk_bf16_f32 v62, v110, v111
	v_cvt_pk_bf16_f32 v63, v66, v67
	v_cvt_pk_bf16_f32 v64, v68, v69
	v_mfma_f32_16x16x32_bf16 v[34:37], v[78:81], v[38:41], v[34:37]
	v_cvt_pk_bf16_f32 v65, v112, v65
	ds_read_b64_tr_b16 v[66:67], v155 offset:0
	ds_read_b64_tr_b16 v[68:69], v155 offset:0x400
	ds_read_b64_tr_b16 v[70:71], v155 offset:0x800
	ds_read_b64_tr_b16 v[72:73], v155 offset:0xc00
	ds_read_b64_tr_b16 v[74:75], v155 offset:0x1000
	ds_read_b64_tr_b16 v[76:77], v155 offset:0x1400
	ds_read_b64_tr_b16 v[78:79], v155 offset:0x1800
	ds_read_b64_tr_b16 v[80:81], v155 offset:0x1c00
	s_waitcnt lgkmcnt(0)
; __device__ __forceinline__ int crow(int r, int hi) { return (r & 3) + 8 * (r >> 2) + 4 * hi; }
; template <int DQ, bool WIN, int LDQ, int LDK> ...
;     ...
;     pv(vb0 + SHM_V); lsum_upd();
;     if (WIN) {
;         if (hi == 0) li_l[r32] = m_ref; asm volatile("s_waitcnt lgkmcnt(0)" ::: "memory");
; #pragma unroll
;         for (int r = 0; r < 16; ++r) lsum[r] += __builtin_amdgcn_exp2f(sink_l2 - li_l[crow(r, hi)]);
;     }
;     float rli[16]; bool fin = true;
; #pragma unroll
;     for (int r = 0; r < 16; ++r) { fin = fin && (lsum[r] < ATT_GUARD) && (lsum[r] > 0.f); rli[r] = __builtin_amdgcn_rcpf(lsum[r]); }
;     if (!__all(fin)) { if (lane == 0) *redo_flag = 1; }
	s_nop 0
	v_mfma_f32_32x32x16_bf16 v[2:17], v[50:53], v[66:69], v[2:17]
	ds_read_b64_tr_b16 v[66:67], v155 offset:0x200
	ds_read_b64_tr_b16 v[68:69], v155 offset:0x600
	v_mfma_f32_32x32x16_bf16 v[2:17], v[54:57], v[70:73], v[2:17]
	ds_read_b64_tr_b16 v[70:71], v155 offset:0xa00
	ds_read_b64_tr_b16 v[72:73], v155 offset:0xe00
	v_mfma_f32_32x32x16_bf16 v[2:17], v[58:61], v[74:77], v[2:17]
	ds_read_b64_tr_b16 v[74:75], v155 offset:0x1200
	ds_read_b64_tr_b16 v[76:77], v155 offset:0x1600
	ds_read_b64_tr_b16 v[82:83], v155 offset:0x1a00
	ds_read_b64_tr_b16 v[84:85], v155 offset:0x1e00
	s_waitcnt lgkmcnt(0)
	v_mfma_f32_32x32x16_bf16 v[2:17], v[62:65], v[78:81], v[2:17]
	v_mfma_f32_16x16x32_bf16 v[34:37], v[50:53], v[38:41], v[34:37]
	v_mfma_f32_16x16x32_bf16 v[34:37], v[54:57], v[38:41], v[34:37]
	v_mfma_f32_16x16x32_bf16 v[34:37], v[58:61], v[38:41], v[34:37]
	v_mfma_f32_16x16x32_bf16 v[34:37], v[62:65], v[38:41], v[34:37]
	v_mfma_f32_32x32x16_bf16 v[18:33], v[50:53], v[66:69], v[18:33]
	v_lshrrev_b32_e32 v98, 4, v151
	v_and_b32_e32 v99, 1, v151
	v_lshlrev_b32_e32 v98, 4, v98
	v_lshl_or_b32 v98, v99, 6, v98
	s_lshl_b32 s0, s20, 3
	s_add_i32 s0, s0, 0x8800
	v_add_u32_e32 v98, s0, v98
	v_lshl_add_u32 v99, v1, 4, s0
	s_nop 1
	ds_write_b128 v98, v[34:37]
	s_waitcnt lgkmcnt(0)
	ds_read_b128 v[34:37], v99
	ds_read_b128 v[38:41], v99 offset:32
	ds_read_b128 v[42:45], v99 offset:64
	ds_read_b128 v[46:49], v99 offset:96
	s_waitcnt lgkmcnt(0)
	v_cmp_gt_f32_e32 vcc, s88, v34
	v_cmp_lt_f32_e64 s[0:1], 0, v34
	s_and_b64 s[22:23], vcc, s[0:1]
	v_cmp_gt_f32_e32 vcc, s88, v35
	v_cmp_lt_f32_e64 s[0:1], 0, v35
	s_and_b64 s[0:1], vcc, s[0:1]
	s_and_b64 s[22:23], s[22:23], s[0:1]
	v_cmp_gt_f32_e32 vcc, s88, v36
	v_cmp_lt_f32_e64 s[0:1], 0, v36
	s_and_b64 s[0:1], vcc, s[0:1]
	s_and_b64 s[22:23], s[22:23], s[0:1]
	v_cmp_gt_f32_e32 vcc, s88, v37
	v_cmp_lt_f32_e64 s[0:1], 0, v37
	s_and_b64 s[0:1], vcc, s[0:1]
	s_and_b64 s[22:23], s[22:23], s[0:1]
	v_cmp_gt_f32_e32 vcc, s88, v38
	v_cmp_lt_f32_e64 s[0:1], 0, v38
	s_and_b64 s[0:1], vcc, s[0:1]
	s_and_b64 s[22:23], s[22:23], s[0:1]
	v_cmp_gt_f32_e32 vcc, s88, v39
	v_cmp_lt_f32_e64 s[0:1], 0, v39
	s_and_b64 s[0:1], vcc, s[0:1]
	s_and_b64 s[22:23], s[22:23], s[0:1]
	v_cmp_gt_f32_e32 vcc, s88, v40
	v_cmp_lt_f32_e64 s[0:1], 0, v40
	s_and_b64 s[0:1], vcc, s[0:1]
	s_and_b64 s[22:23], s[22:23], s[0:1]
	v_cmp_gt_f32_e32 vcc, s88, v41
	v_cmp_lt_f32_e64 s[0:1], 0, v41
	s_and_b64 s[0:1], vcc, s[0:1]
	v_mfma_f32_32x32x16_bf16 v[18:33], v[54:57], v[70:73], v[18:33]
	s_and_b64 s[22:23], s[22:23], s[0:1]
	v_cmp_gt_f32_e32 vcc, s88, v42
	v_cmp_lt_f32_e64 s[0:1], 0, v42
	s_and_b64 s[0:1], vcc, s[0:1]
	s_and_b64 s[22:23], s[22:23], s[0:1]
	v_cmp_gt_f32_e32 vcc, s88, v43
	v_cmp_lt_f32_e64 s[0:1], 0, v43
	s_and_b64 s[0:1], vcc, s[0:1]
	s_and_b64 s[22:23], s[22:23], s[0:1]
	v_cmp_gt_f32_e32 vcc, s88, v44
	v_cmp_lt_f32_e64 s[0:1], 0, v44
	s_and_b64 s[0:1], vcc, s[0:1]
	s_and_b64 s[22:23], s[22:23], s[0:1]
	v_cmp_gt_f32_e32 vcc, s88, v45
	v_cmp_lt_f32_e64 s[0:1], 0, v45
	s_and_b64 s[0:1], vcc, s[0:1]
	v_mfma_f32_32x32x16_bf16 v[18:33], v[58:61], v[74:77], v[18:33]
	s_and_b64 s[22:23], s[22:23], s[0:1]
	v_cmp_gt_f32_e32 vcc, s88, v46
	v_cmp_lt_f32_e64 s[0:1], 0, v46
	s_and_b64 s[0:1], vcc, s[0:1]
	s_and_b64 s[22:23], s[22:23], s[0:1]
	v_cmp_gt_f32_e32 vcc, s88, v47
	v_cmp_lt_f32_e64 s[0:1], 0, v47
	s_and_b64 s[0:1], vcc, s[0:1]
	s_and_b64 s[22:23], s[22:23], s[0:1]
	v_cmp_gt_f32_e32 vcc, s88, v48
	v_cmp_lt_f32_e64 s[0:1], 0, v48
	s_and_b64 s[0:1], vcc, s[0:1]
	s_and_b64 s[22:23], s[22:23], s[0:1]
	v_cmp_gt_f32_e32 vcc, s88, v49
	v_cmp_lt_f32_e64 s[0:1], 0, v49
	s_and_b64 s[0:1], vcc, s[0:1]
	v_mfma_f32_32x32x16_bf16 v[18:33], v[62:65], v[82:85], v[18:33]
	s_and_b64 s[0:1], s[22:23], s[0:1]
	v_cndmask_b32_e64 v50, 0, 1, s[0:1]
	v_cmp_ne_u32_e32 vcc, 0, v50
	s_cmp_eq_u64 vcc, exec
	s_cselect_b64 s[0:1], -1, 0
	v_cndmask_b32_e64 v50, 0, 1, s[0:1]
	v_or_b32_e32 v50, v151, v50
	v_cmp_eq_u32_e32 vcc, 0, v50
	s_and_saveexec_b64 s[0:1], vcc
	s_cbranch_execz .LBB0_497
	s_mov_b64 s[22:23], src_shared_base
	s_cmp_lg_u32 s97, -1
	s_cselect_b32 s21, s97, 0
	s_cselect_b32 s22, s23, 0
	v_mov_b32_e32 v50, s21
	v_mov_b32_e32 v51, s22
	flat_store_dword v[50:51], v152 sc0 sc1
	s_waitcnt vmcnt(0)
